# attnA QK section: two counted LDS waits instead of eight, redundant s_nop in the DMA issue removed (8 fewer issue slots per step)
# speedup vs baseline: 1.0050x; 1.0050x over previous
; #define LAS __attribute__((address_space(3)))
; __device__ __forceinline__ void attnA_unit(const P2Ctx& C, int b, int h, int qb) {
;     LAS unsigned char* lds = C.lds; const int lane = C.lane, wid = C.wid, pf = C.pf;
;     const int comp = wid >> 2, qs = wid & 3, r32 = lane & 31, hi = lane >> 5;
;     const int q0 = qb * 128, trow0 = b * SEQ;
;     const int qpos = q0 + qs * 32 + r32; const size_t qrow = (size_t)(trow0 + qpos);
;     const int qcw = (q0 + qs * 32) >> 6, ntw = qcw + 1, NT = 2 * qb + 2;
;     const LAS float* lut = (const LAS float*)(lds + LUT_OFF) + h * 256;
;     const float lam = *(const LAS float*)(lds + LAM_OFF);
;     bf16x8 qf[4];
; #pragma unroll
;     for (int ds = 0; ds < 4; ++ds) qf[ds] = *(const bf16x8*)(C.Q + qrow * DM + h * 128 + comp * 64 + ds * 16 + hi * 8);
;     const int kkey = 8 * wid + (lane >> 3), kchs = (lane & 7) ^ ((kkey >> 1) & 7);
;     const bf16_t* ksrc = C.Kb + ((size_t)trow0 + kkey) * DM + h * 128 + kchs * 8;
;     const bf16_t* vsrc[2];
; #pragma unroll
;     for (int i = 0; i < 2; ++i) { const int p = 2 * wid + i, kg = p >> 1, cbv = 2 * (p & 1) + (lane >> 5), vkey = kg * 8 + ((lane >> 2) & 7), vch = cbv * 4 + (lane & 3);
;         vsrc[i] = C.Vb + ((size_t)trow0 + vkey) * DM + h * 128 + vch * 8; }
;     ...
;     A_DMA(0); A_DMA(1);
.LBB0_572:
	s_andn2_b64 vcc, exec, s[6:7]
	s_cbranch_vccnz .LBB0_614
	s_sub_i32 s6, s37, 32
	s_lshr_b32 s11, s6, 4
	s_and_b32 s6, s6, 15
	s_sub_i32 s10, 15, s6
	s_lshr_b32 s8, s83, 2
	s_and_b32 s9, s83, 3
	s_lshl_b32 s12, s10, 1
	s_add_i32 s12, s12, 2
	s_lshr_b32 s6, s9, 1
	s_lshl_b32 s13, s10, 1
	s_add_i32 s13, s13, s6
	s_add_i32 s13, s13, 1
	s_lshl_b32 s22, s83, 10
	s_lshl_b32 s23, s83, 11
	s_add_i32 s23, s23, 0x4000
	s_lshl_b32 s6, s10, 7
	s_lshl_b32 s7, s9, 5
	s_add_i32 s15, s6, s7
	s_add_i32 s26, s15, 0xffffff01
	s_mov_b32 s25, 0
	v_and_b32_e32 v100, 31, v219
	v_lshrrev_b32_e32 v101, 5, v219
	s_load_dwordx2 s[20:21], s[62:63], 0x80
	v_lshlrev_b32_e32 v107, 4, v196
	s_waitcnt lgkmcnt(0)
	v_cmp_gt_u32_e32 vcc, 32, v196
	s_and_saveexec_b64 s[6:7], vcc
	global_load_dwordx4 v[108:111], v107, s[20:21]
	s_or_b64 exec, exec, s[6:7]
	s_lshl_b32 s6, s11, 11
	s_add_i32 s6, s6, s15
	s_lshl_b32 s6, s6, 11
	s_lshl_b32 s7, s81, 1
	s_add_i32 s6, s6, s7
	s_lshl_b32 s7, s8, 7
	s_add_i32 s6, s6, s7
	s_add_u32 s20, s76, s6
	s_addc_u32 s21, s77, 0
	v_lshlrev_b32_e32 v102, 11, v100
	v_lshl_add_u32 v102, v101, 4, v102
	global_load_dwordx4 v[164:167], v102, s[20:21]
	global_load_dwordx4 v[168:171], v102, s[20:21] offset:32
	global_load_dwordx4 v[172:175], v102, s[20:21] offset:64
	global_load_dwordx4 v[176:179], v102, s[20:21] offset:96
	s_lshl_b32 s6, s11, 22
	s_lshl_b32 s7, s81, 1
	s_add_i32 s6, s6, s7
	s_add_u32 s16, s72, s6
	s_addc_u32 s17, s73, 0
	s_add_u32 s18, s74, s6
	s_addc_u32 s19, s75, 0
	s_mov_b32 s24, 0
	v_lshrrev_b32_e32 v103, 3, v219
	s_lshl_b32 s6, s83, 3
	v_add_u32_e32 v103, s6, v103
	v_bfe_u32 v104, v103, 1, 3
	v_and_b32_e32 v105, 7, v219
	v_xor_b32_e32 v104, v104, v105
	v_lshlrev_b32_e32 v104, 4, v104
	v_lshl_add_u32 v197, v103, 11, v104
	v_bfe_u32 v103, v219, 2, 3
	v_add_u32_e32 v103, s6, v103
	v_and_b32_e32 v104, 3, v219
	v_lshlrev_b32_e32 v104, 4, v104
	v_lshl_add_u32 v104, v101, 6, v104
	v_lshl_add_u32 v198, v103, 11, v104
	s_and_b32 s6, s24, 3
	s_lshl_b32 s6, s6, 15
	s_add_i32 s7, s6, s22
	s_mov_b32 m0, s7
	s_add_u32 s20, s16, 0x80
	s_addc_u32 s21, s17, 0
	s_add_i32 s29, s6, s23
	global_load_lds_dwordx4 v197, s[16:17]
	s_add_i32 m0, s7, 0x2000
	s_add_u32 s16, s16, 0x20000
	s_addc_u32 s17, s17, 0
	global_load_lds_dwordx4 v197, s[20:21]
	s_mov_b32 m0, s29
	s_add_u32 s20, s18, 0x80
	s_addc_u32 s21, s19, 0
	global_load_lds_dwordx4 v198, s[18:19]
	s_add_i32 m0, s29, 0x400
	s_add_u32 s18, s18, 0x20000
	s_addc_u32 s19, s19, 0
	s_add_i32 s24, s24, 1
	global_load_lds_dwordx4 v198, s[20:21]
	s_and_b32 s6, s24, 3
	s_lshl_b32 s6, s6, 15
	s_add_i32 s7, s6, s22
	s_mov_b32 m0, s7
	s_add_u32 s20, s16, 0x80
	s_addc_u32 s21, s17, 0
	s_add_i32 s29, s6, s23
	global_load_lds_dwordx4 v197, s[16:17]
	s_add_i32 m0, s7, 0x2000
	s_add_u32 s16, s16, 0x20000
	s_addc_u32 s17, s17, 0
	global_load_lds_dwordx4 v197, s[20:21]
	s_mov_b32 m0, s29
	s_add_u32 s20, s18, 0x80
	s_addc_u32 s21, s19, 0
	global_load_lds_dwordx4 v198, s[18:19]
	s_add_i32 m0, s29, 0x400
	s_add_u32 s18, s18, 0x20000
	s_addc_u32 s19, s19, 0
	s_add_i32 s24, s24, 1
	global_load_lds_dwordx4 v198, s[20:21]
	v_bfe_u32 v103, v100, 1, 3
	v_lshlrev_b32_e32 v104, 7, v100
	s_lshl_b32 s6, s8, 13
	v_add_u32_e32 v104, s6, v104
	v_or_b32_e32 v105, 0, v101
	v_xor_b32_e32 v105, v105, v103
	v_lshl_add_u32 v200, v105, 4, v104
	v_or_b32_e32 v105, 2, v101
	v_xor_b32_e32 v105, v105, v103
	v_lshl_add_u32 v201, v105, 4, v104
	v_or_b32_e32 v105, 4, v101
	v_xor_b32_e32 v105, v105, v103
	v_lshl_add_u32 v202, v105, 4, v104
	v_or_b32_e32 v105, 6, v101
	v_xor_b32_e32 v105, v105, v103
	v_lshl_add_u32 v203, v105, 4, v104
	v_bfe_u32 v103, v219, 2, 2
	v_lshl_add_u32 v103, v101, 2, v103
	v_lshlrev_b32_e32 v103, 6, v103
	v_bfe_u32 v104, v219, 4, 1
	v_lshl_add_u32 v103, v104, 5, v103
	v_and_b32_e32 v104, 3, v219
	v_lshl_add_u32 v103, v104, 3, v103
	v_add_u32_e32 v204, 0x4000, v103
	s_sub_i32 s6, 0x120, s15
	s_lshl_b32 s6, s6, 2
	s_add_i32 s6, s6, 0x22400
	v_lshlrev_b32_e32 v103, 4, v101
	v_lshlrev_b32_e32 v104, 2, v100
	v_sub_u32_e32 v103, v103, v104
	v_add_u32_e32 v236, s6, v103
	v_cmp_gt_u32_e32 vcc, 0x160, v196
	s_and_saveexec_b64 s[6:7], vcc
	s_cbranch_execz .LaA_padskip_1
	v_subrev_u32_e32 v103, 0x60, v196
	v_max_i32_e32 v104, 0, v103
	v_lshl_add_u32 v104, v104, 2, s42
	ds_read_b32 v105, v104
	v_cmp_gt_i32_e32 vcc, 0, v103
	v_mov_b32_e32 v106, 0x22400
	v_lshl_add_u32 v104, v196, 2, v106
	s_waitcnt lgkmcnt(0)
	v_cndmask_b32_e64 v105, v105, 0, vcc
	ds_write_b32 v104, v105
; #define A_WAITBAR(ahead) do { if ((ahead) >= 2) asm volatile("s_waitcnt vmcnt(8)" ::: "memory"); else if ((ahead) == 1) asm volatile("s_waitcnt vmcnt(4)" ::: "memory"); else asm volatile("s_waitcnt vmcnt(0)" ::: "memory"); \
;         __builtin_amdgcn_s_barrier(); asm volatile("" ::: "memory"); } while (0)
; __device__ __forceinline__ void attnA_unit(const P2Ctx& C, int b, int h, int qb) {
;     ...
;     f32x16 o[4];
; #pragma unroll
;     for (int cb = 0; cb < 4; ++cb)
; #pragma unroll
;         for (int r = 0; r < 16; ++r) o[cb][r] = 0.f;
;     float mhat = 0.f, l = 0.f;
;     bf16x8 pf_[4];
; #pragma unroll
;     for (int i = 0; i < 4; ++i) pf_[i] = (bf16x8){0, 0, 0, 0, 0, 0, 0, 0};
;     ...
;     A_DMA(0); A_DMA(1);
;     A_WAITBAR(1);
;     { if (2 < NT && !(pf & 16)) A_DMA(2);
.LaA_padskip_1:
	s_or_b64 exec, exec, s[6:7]
	v_mov_b32_e32 v4, 0
	v_mov_b32_e32 v5, 0
	v_mov_b32_e32 v6, 0
	v_mov_b32_e32 v7, 0
	v_mov_b32_e32 v8, 0
	v_mov_b32_e32 v9, 0
	v_mov_b32_e32 v10, 0
	v_mov_b32_e32 v11, 0
	v_mov_b32_e32 v12, 0
	v_mov_b32_e32 v13, 0
	v_mov_b32_e32 v14, 0
	v_mov_b32_e32 v15, 0
	v_mov_b32_e32 v16, 0
	v_mov_b32_e32 v17, 0
	v_mov_b32_e32 v18, 0
	v_mov_b32_e32 v19, 0
	v_mov_b32_e32 v20, 0
	v_mov_b32_e32 v21, 0
	v_mov_b32_e32 v22, 0
	v_mov_b32_e32 v23, 0
	v_mov_b32_e32 v24, 0
	v_mov_b32_e32 v25, 0
	v_mov_b32_e32 v26, 0
	v_mov_b32_e32 v27, 0
	v_mov_b32_e32 v28, 0
	v_mov_b32_e32 v29, 0
	v_mov_b32_e32 v30, 0
	v_mov_b32_e32 v31, 0
	v_mov_b32_e32 v32, 0
	v_mov_b32_e32 v33, 0
	v_mov_b32_e32 v34, 0
	v_mov_b32_e32 v35, 0
	v_mov_b32_e32 v36, 0
	v_mov_b32_e32 v37, 0
	v_mov_b32_e32 v38, 0
	v_mov_b32_e32 v39, 0
	v_mov_b32_e32 v40, 0
	v_mov_b32_e32 v41, 0
	v_mov_b32_e32 v42, 0
	v_mov_b32_e32 v43, 0
	v_mov_b32_e32 v44, 0
	v_mov_b32_e32 v45, 0
	v_mov_b32_e32 v46, 0
	v_mov_b32_e32 v47, 0
	v_mov_b32_e32 v48, 0
	v_mov_b32_e32 v49, 0
	v_mov_b32_e32 v50, 0
	v_mov_b32_e32 v51, 0
	v_mov_b32_e32 v52, 0
	v_mov_b32_e32 v53, 0
	v_mov_b32_e32 v54, 0
	v_mov_b32_e32 v55, 0
	v_mov_b32_e32 v56, 0
	v_mov_b32_e32 v57, 0
	v_mov_b32_e32 v58, 0
	v_mov_b32_e32 v59, 0
	v_mov_b32_e32 v60, 0
	v_mov_b32_e32 v61, 0
	v_mov_b32_e32 v62, 0
	v_mov_b32_e32 v63, 0
	v_mov_b32_e32 v64, 0
	v_mov_b32_e32 v65, 0
	v_mov_b32_e32 v66, 0
	v_mov_b32_e32 v67, 0
	v_mov_b32_e32 v220, 0
	v_mov_b32_e32 v221, 0
	v_mov_b32_e32 v222, 0
	v_mov_b32_e32 v223, 0
	v_mov_b32_e32 v224, 0
	v_mov_b32_e32 v225, 0
	v_mov_b32_e32 v226, 0
	v_mov_b32_e32 v227, 0
	v_mov_b32_e32 v228, 0
	v_mov_b32_e32 v229, 0
	v_mov_b32_e32 v230, 0
	v_mov_b32_e32 v231, 0
	v_mov_b32_e32 v232, 0
	v_mov_b32_e32 v233, 0
	v_mov_b32_e32 v234, 0
	v_mov_b32_e32 v235, 0
	v_mov_b32_e32 v240, 0
	v_mov_b32_e32 v241, 0
	s_mov_b32 s14, 0
	s_waitcnt vmcnt(4) lgkmcnt(0)
	v_cmp_gt_u32_e32 vcc, 32, v196
	v_add_u32_e32 v107, 0x22a00, v107
	s_and_saveexec_b64 s[6:7], vcc
	ds_write_b128 v107, v[108:111]
	s_or_b64 exec, exec, s[6:7]
	s_waitcnt lgkmcnt(0)
	s_barrier
	s_cmp_lt_u32 s24, s12
	s_cbranch_scc0 .LaA_nodma_2
	s_and_b32 s6, s24, 3
	s_lshl_b32 s6, s6, 15
	s_add_i32 s7, s6, s22
	s_mov_b32 m0, s7
	s_add_u32 s20, s16, 0x80
	s_addc_u32 s21, s17, 0
	s_add_i32 s29, s6, s23
	global_load_lds_dwordx4 v197, s[16:17]
	s_add_i32 m0, s7, 0x2000
	s_add_u32 s16, s16, 0x20000
	s_addc_u32 s17, s17, 0
	global_load_lds_dwordx4 v197, s[20:21]
	s_mov_b32 m0, s29
	s_add_u32 s20, s18, 0x80
	s_addc_u32 s21, s19, 0
	global_load_lds_dwordx4 v198, s[18:19]
	s_add_i32 m0, s29, 0x400
	s_add_u32 s18, s18, 0x20000
	s_addc_u32 s19, s19, 0
	s_add_i32 s24, s24, 1
	global_load_lds_dwordx4 v198, s[20:21]

; #define LAS __attribute__((address_space(3)))
; __device__ __forceinline__ float fexp2(float x) { return __builtin_amdgcn_exp2f(x); }
; #define MFMA32(a, b, c) __builtin_amdgcn_mfma_f32_32x32x16_bf16((a), (b), (c), 0, 0, 0)
; __device__ __forceinline__ bf16x8 v_build(const VRaw& r, int ks) { return (bf16x8){r.lo[ks][0], r.lo[ks][1], r.lo[ks][2], r.lo[ks][3], r.hv[ks][0], r.hv[ks][1], r.hv[ks][2], r.hv[ks][3]}; }
; #define A_MAX() \
;         float mx = fmaxf(s[0][0], s[1][0]); \
;         _Pragma("unroll") for (int r = 1; r < 16; ++r) mx = fmaxf(fmaxf(mx, s[0][r]), s[1][r]); \
;         mx = fmaxf(mx, __shfl_xor(mx, 32));
; __device__ __forceinline__ void attnA_unit(const P2Ctx& C, int b, int h, int qb) {
;     ...
;     for (int kt = 1; kt < NT; ++kt) {
;         if (kt + 2 < NT && !(pf & 16)) A_DMA(kt + 2);
;         if (kt < ntw) {
;             A_QK(kt)
;             if (!(pf & 4)) {
;             const LAS unsigned char* vimg = lds + ((kt - 1) & 3) * 32768 + 16384;
;             VRaw va;
;             v_issue<4>(vimg, 0, lane, va);
;             A_MAX()
;             float fres = 1.0f; bool resc = false;
;             if (__any(mx > ATHR)) {
;                 const float dl = fmaxf(mx, 0.f);
;                 mhat += dl;
;                 fres = fexp2(-dl); resc = true;
; #pragma unroll
;                 for (int kb2 = 0; kb2 < 2; ++kb2)
; #pragma unroll
;                     for (int r = 0; r < 16; ++r) s[kb2][r] -= dl;
;             }
;             float ps = 0.f;
;             v_wait(va);
;             __builtin_amdgcn_s_setprio(1);
; #pragma unroll
;             for (int ks = 0; ks < 4; ++ks) o[0] = MFMA32(v_build(va, ks), pf_[ks], o[0]);
.LaA_loop:
	s_cmp_lt_u32 s14, s13
	s_cbranch_scc0 .LaA_pvonly
	s_and_b32 s6, s14, 3
	s_lshl_b32 s6, s6, 15
	s_add_i32 s7, s14, -1
	s_and_b32 s7, s7, 3
	s_lshl_b32 s7, s7, 15
	v_add_u32_e32 v248, s6, v200
	v_add_u32_e32 v249, s6, v201
	v_add_u32_e32 v250, s6, v202
	v_add_u32_e32 v251, s6, v203
	v_add_u32_e32 v237, s7, v204
	ds_read_b128 v[100:103], v248
	ds_read_b128 v[104:107], v248 offset:4096
	ds_read_b128 v[108:111], v249
	ds_read_b128 v[112:115], v249 offset:4096
	ds_read_b128 v[116:119], v250
	ds_read_b128 v[120:123], v250 offset:4096
	ds_read_b128 v[124:127], v251
	ds_read_b128 v[128:131], v251 offset:4096
	s_cmp_lt_u32 s24, s12
	s_cbranch_scc0 .LaA_nodma_7
	s_and_b32 s6, s24, 3
	s_lshl_b32 s6, s6, 15
	s_add_i32 s7, s6, s22
	s_mov_b32 m0, s7
	s_add_u32 s20, s16, 0x80
	s_addc_u32 s21, s17, 0
	s_add_i32 s29, s6, s23
	global_load_lds_dwordx4 v197, s[16:17]
	s_add_i32 m0, s7, 0x2000
	s_add_u32 s16, s16, 0x20000
	s_addc_u32 s17, s17, 0
	global_load_lds_dwordx4 v197, s[20:21]
	s_mov_b32 m0, s29
	s_add_u32 s20, s18, 0x80
	s_addc_u32 s21, s19, 0
	global_load_lds_dwordx4 v198, s[18:19]
	s_add_i32 m0, s29, 0x400
	s_add_u32 s18, s18, 0x20000
	s_addc_u32 s19, s19, 0
	s_add_i32 s24, s24, 1
	global_load_lds_dwordx4 v198, s[20:21]
.LaA_nodma_7:
	s_waitcnt lgkmcnt(4)
	v_mfma_f32_32x32x16_bf16 v[68:83], v[100:103], v[164:167], v[220:235]
	ds_read_b64_tr_b16 v[132:133], v237 offset:0
	ds_read_b64_tr_b16 v[134:135], v237 offset:2048
	v_mfma_f32_32x32x16_bf16 v[84:99], v[104:107], v[164:167], v[220:235]
	ds_read_b64_tr_b16 v[136:137], v237 offset:4096
	ds_read_b64_tr_b16 v[138:139], v237 offset:6144
	v_mfma_f32_32x32x16_bf16 v[68:83], v[108:111], v[168:171], v[68:83]
	ds_read_b64_tr_b16 v[140:141], v237 offset:8192
	ds_read_b64_tr_b16 v[142:143], v237 offset:10240
	v_mfma_f32_32x32x16_bf16 v[84:99], v[112:115], v[168:171], v[84:99]
	ds_read_b64_tr_b16 v[144:145], v237 offset:12288
	ds_read_b64_tr_b16 v[146:147], v237 offset:14336
	s_waitcnt lgkmcnt(8)
	v_mfma_f32_32x32x16_bf16 v[68:83], v[116:119], v[172:175], v[68:83]
	v_mfma_f32_32x32x16_bf16 v[84:99], v[120:123], v[172:175], v[84:99]
	v_mfma_f32_32x32x16_bf16 v[68:83], v[124:127], v[176:179], v[68:83]
	v_mfma_f32_32x32x16_bf16 v[84:99], v[128:131], v[176:179], v[84:99]
	s_waitcnt lgkmcnt(0)
	ds_read_b64_tr_b16 v[148:149], v237 offset:512
	ds_read_b64_tr_b16 v[150:151], v237 offset:2560
	v_mfma_f32_32x32x16_bf16 v[4:19], v[132:135], v[180:183], v[4:19]
	ds_read_b64_tr_b16 v[152:153], v237 offset:4608
	ds_read_b64_tr_b16 v[154:155], v237 offset:6656
	ds_read_b64_tr_b16 v[156:157], v237 offset:8704
	v_mfma_f32_32x32x16_bf16 v[4:19], v[136:139], v[184:187], v[4:19]
	ds_read_b64_tr_b16 v[158:159], v237 offset:10752
	ds_read_b64_tr_b16 v[160:161], v237 offset:12800
	ds_read_b64_tr_b16 v[162:163], v237 offset:14848
	v_mfma_f32_32x32x16_bf16 v[4:19], v[140:143], v[188:191], v[4:19]
	v_mfma_f32_32x32x16_bf16 v[4:19], v[144:147], v[192:195], v[4:19]
	s_lshl_b32 s6, s14, 6
	s_cmp_gt_i32 s6, s26
	s_cbranch_scc1 .LaA_near_8

; __device__ __forceinline__ void attnA_unit(const P2Ctx& C, int b, int h, int qb) {
;     ...
;     for (int kt = 1; kt < NT; ++kt) {
;         if (kt + 2 < NT && !(pf & 16)) A_DMA(kt + 2);
;     ...
;         } else if (kt - 1 < ntw && !(pf & 2)) { A_PV(kt - 1); }
.LaA_pvonly:
	s_cmp_lt_u32 s24, s12
	s_cbranch_scc0 .LaA_nodma_13
	s_and_b32 s6, s24, 3
	s_lshl_b32 s6, s6, 15
	s_add_i32 s7, s6, s22
	s_mov_b32 m0, s7
	s_add_u32 s20, s16, 0x80
	s_addc_u32 s21, s17, 0
	s_add_i32 s29, s6, s23
	global_load_lds_dwordx4 v197, s[16:17]
	s_add_i32 m0, s7, 0x2000
	s_add_u32 s16, s16, 0x20000
	s_addc_u32 s17, s17, 0
	global_load_lds_dwordx4 v197, s[20:21]
	s_mov_b32 m0, s29
	s_add_u32 s20, s18, 0x80
	s_addc_u32 s21, s19, 0
	global_load_lds_dwordx4 v198, s[18:19]
	s_add_i32 m0, s29, 0x400
	s_add_u32 s18, s18, 0x20000
	s_addc_u32 s19, s19, 0
	s_add_i32 s24, s24, 1
	global_load_lds_dwordx4 v198, s[20:21]

; #define LAS __attribute__((address_space(3)))
; __device__ __forceinline__ void attnA_unit(const P2Ctx& C, int b, int h, int qb) {
;     ...
;     l += __shfl_xor(l, 32);
;     const float inv = 1.0f / l;
;     LAS float* X2 = (LAS float*)(lds + 65536);
;     if (comp == 1) {
; #pragma unroll
;         for (int cb = 0; cb < 4; ++cb)
; #pragma unroll
;             for (int r = 0; r < 16; ++r) X2[((qs * 4 + cb) * 16 + r) * 64 + lane] = o[cb][r] * inv;
;     }
;     __syncthreads();
.LaA_nofinalpv_14:
	s_waitcnt lgkmcnt(0)
	s_barrier
	v_mov_b32_e32 v243, v241
	s_nop 1
	v_permlane32_swap_b32 v243, v241
	v_add_f32_e32 v241, v243, v241
	v_rcp_f32_e32 v241, v241
	s_lshl_b32 s6, s9, 14
	s_add_i32 s6, s6, 0x10000
	v_lshlrev_b32_e32 v2, 2, v219
	v_add_u32_e32 v2, s6, v2
	s_cmp_eq_u32 s8, 0
	s_cbranch_scc1 .LaA_comp0_15
	s_nop 7
	s_nop 3
	v_mul_f32_e32 v68, v4, v241
	ds_write_b32 v2, v68 offset:0
	v_mul_f32_e32 v69, v5, v241
	ds_write_b32 v2, v69 offset:256
	v_mul_f32_e32 v68, v6, v241
	ds_write_b32 v2, v68 offset:512
	v_mul_f32_e32 v69, v7, v241
	ds_write_b32 v2, v69 offset:768
	v_mul_f32_e32 v68, v8, v241
	ds_write_b32 v2, v68 offset:1024
	v_mul_f32_e32 v69, v9, v241
	ds_write_b32 v2, v69 offset:1280
	v_mul_f32_e32 v68, v10, v241
	ds_write_b32 v2, v68 offset:1536
	v_mul_f32_e32 v69, v11, v241
	ds_write_b32 v2, v69 offset:1792
	v_mul_f32_e32 v68, v12, v241
	ds_write_b32 v2, v68 offset:2048
	v_mul_f32_e32 v69, v13, v241
	ds_write_b32 v2, v69 offset:2304
	v_mul_f32_e32 v68, v14, v241
	ds_write_b32 v2, v68 offset:2560
	v_mul_f32_e32 v69, v15, v241
	ds_write_b32 v2, v69 offset:2816
	v_mul_f32_e32 v68, v16, v241
	ds_write_b32 v2, v68 offset:3072
	v_mul_f32_e32 v69, v17, v241
	ds_write_b32 v2, v69 offset:3328
	v_mul_f32_e32 v68, v18, v241
	ds_write_b32 v2, v68 offset:3584
	v_mul_f32_e32 v69, v19, v241
	ds_write_b32 v2, v69 offset:3840
	v_mul_f32_e32 v68, v20, v241
	ds_write_b32 v2, v68 offset:4096
	v_mul_f32_e32 v69, v21, v241
	ds_write_b32 v2, v69 offset:4352
	v_mul_f32_e32 v68, v22, v241
	ds_write_b32 v2, v68 offset:4608
	v_mul_f32_e32 v69, v23, v241
	ds_write_b32 v2, v69 offset:4864
	v_mul_f32_e32 v68, v24, v241
	ds_write_b32 v2, v68 offset:5120
	v_mul_f32_e32 v69, v25, v241
	ds_write_b32 v2, v69 offset:5376
	v_mul_f32_e32 v68, v26, v241
	ds_write_b32 v2, v68 offset:5632
	v_mul_f32_e32 v69, v27, v241
	ds_write_b32 v2, v69 offset:5888
	v_mul_f32_e32 v68, v28, v241
	ds_write_b32 v2, v68 offset:6144
	v_mul_f32_e32 v69, v29, v241
	ds_write_b32 v2, v69 offset:6400
	v_mul_f32_e32 v68, v30, v241
	ds_write_b32 v2, v68 offset:6656
	v_mul_f32_e32 v69, v31, v241
	ds_write_b32 v2, v69 offset:6912
	v_mul_f32_e32 v68, v32, v241
	ds_write_b32 v2, v68 offset:7168
	v_mul_f32_e32 v69, v33, v241
	ds_write_b32 v2, v69 offset:7424
	v_mul_f32_e32 v68, v34, v241
	ds_write_b32 v2, v68 offset:7680
	v_mul_f32_e32 v69, v35, v241
	ds_write_b32 v2, v69 offset:7936
	v_mul_f32_e32 v68, v36, v241
	ds_write_b32 v2, v68 offset:8192
	v_mul_f32_e32 v69, v37, v241
	ds_write_b32 v2, v69 offset:8448
	v_mul_f32_e32 v68, v38, v241
	ds_write_b32 v2, v68 offset:8704
	v_mul_f32_e32 v69, v39, v241
	ds_write_b32 v2, v69 offset:8960
	v_mul_f32_e32 v68, v40, v241
	ds_write_b32 v2, v68 offset:9216
	v_mul_f32_e32 v69, v41, v241
	ds_write_b32 v2, v69 offset:9472
	v_mul_f32_e32 v68, v42, v241
	ds_write_b32 v2, v68 offset:9728
	v_mul_f32_e32 v69, v43, v241
	ds_write_b32 v2, v69 offset:9984
	v_mul_f32_e32 v68, v44, v241
	ds_write_b32 v2, v68 offset:10240
	v_mul_f32_e32 v69, v45, v241
	ds_write_b32 v2, v69 offset:10496
	v_mul_f32_e32 v68, v46, v241
	ds_write_b32 v2, v68 offset:10752
	v_mul_f32_e32 v69, v47, v241
	ds_write_b32 v2, v69 offset:11008
	v_mul_f32_e32 v68, v48, v241
	ds_write_b32 v2, v68 offset:11264
	v_mul_f32_e32 v69, v49, v241
	ds_write_b32 v2, v69 offset:11520
	v_mul_f32_e32 v68, v50, v241
	ds_write_b32 v2, v68 offset:11776
	v_mul_f32_e32 v69, v51, v241
	ds_write_b32 v2, v69 offset:12032
	v_mul_f32_e32 v68, v52, v241
	ds_write_b32 v2, v68 offset:12288
	v_mul_f32_e32 v69, v53, v241
	ds_write_b32 v2, v69 offset:12544
	v_mul_f32_e32 v68, v54, v241
	ds_write_b32 v2, v68 offset:12800
	v_mul_f32_e32 v69, v55, v241
	ds_write_b32 v2, v69 offset:13056
	v_mul_f32_e32 v68, v56, v241
	ds_write_b32 v2, v68 offset:13312
	v_mul_f32_e32 v69, v57, v241
	ds_write_b32 v2, v69 offset:13568
	v_mul_f32_e32 v68, v58, v241
	ds_write_b32 v2, v68 offset:13824
	v_mul_f32_e32 v69, v59, v241
	ds_write_b32 v2, v69 offset:14080
	v_mul_f32_e32 v68, v60, v241
	ds_write_b32 v2, v68 offset:14336
	v_mul_f32_e32 v69, v61, v241
	ds_write_b32 v2, v69 offset:14592
	v_mul_f32_e32 v68, v62, v241
	ds_write_b32 v2, v68 offset:14848
	v_mul_f32_e32 v69, v63, v241
	ds_write_b32 v2, v69 offset:15104
	v_mul_f32_e32 v68, v64, v241
	ds_write_b32 v2, v68 offset:15360
	v_mul_f32_e32 v69, v65, v241
	ds_write_b32 v2, v69 offset:15616
	v_mul_f32_e32 v68, v66, v241
	ds_write_b32 v2, v68 offset:15872
	v_mul_f32_e32 v69, v67, v241
	ds_write_b32 v2, v69 offset:16128
	s_waitcnt lgkmcnt(0)
	s_barrier
	s_branch .LaA_epiend_16
; __device__ __forceinline__ void attnA_unit(const P2Ctx& C, int b, int h, int qb) {
;     ...
;     if (comp == 1) {
; #pragma unroll
;         for (int cb = 0; cb < 4; ++cb)
; #pragma unroll
;             for (int r = 0; r < 16; ++r) X2[((qs * 4 + cb) * 16 + r) * 64 + lane] = o[cb][r] * inv;
;     }
;     __syncthreads();
;     if (comp == 0) {
; #pragma unroll
;         for (int cb = 0; cb < 4; ++cb)
; #pragma unroll
;             for (int r = 0; r < 16; ++r) o[cb][r] = o[cb][r] * inv - lam * X2[((qs * 4 + cb) * 16 + r) * 64 + lane];
;         subln_store(o, C.a->in[I_SUBG], C.AO + qrow * DM + h * 128, lane);
;     }
	s_nop 0
	s_nop 0
	s_nop 0
	s_nop 0
	s_nop 0
	s_nop 0
	s_nop 0
	s_nop 0
	s_nop 0
	s_nop 0
	s_nop 0
	s_nop 0
	s_nop 0
	s_nop 0
	s_nop 0
	s_nop 0
	s_nop 0
	s_nop 0
	s_nop 0
	s_nop 0
	s_nop 0
	s_nop 0
	s_nop 0
	s_nop 0
	s_nop 0
	s_nop 0
	s_nop 0
	s_nop 0
	s_nop 0
	s_nop 0
	s_nop 0
	s_nop 0
	s_nop 0
	s_nop 0
	s_nop 0
	s_nop 0
	s_nop 0
	s_nop 0
	s_nop 0
	s_nop 0
	s_nop 0
	s_nop 0
	s_nop 0
	s_nop 0
	s_nop 0
	s_nop 0
	s_nop 0
	s_nop 0
	s_nop 0
	s_nop 0
	s_nop 0
	s_nop 0
	s_nop 0
	s_nop 0
	s_nop 0
	s_nop 0
	s_nop 0
	s_nop 0
	s_nop 0
	s_nop 0
	s_nop 0
	s_nop 0
	s_nop 0
	s_nop 0
	s_nop 0
	s_nop 0
	s_nop 0
	s_nop 0
	s_nop 0
	s_nop 0
	s_nop 0
	s_nop 0
	s_nop 0
	s_nop 0
	s_nop 0
	s_nop 0
	s_nop 0
	s_nop 0
	s_nop 0
	s_nop 0
	s_nop 0
	s_nop 0
	s_nop 0
	s_nop 0
	s_nop 0
	s_nop 0
	s_nop 0
	s_nop 0
	s_nop 0
	s_nop 0
	s_nop 0
	s_nop 0
	s_nop 0
	s_nop 0
	s_nop 0
	s_nop 0
	s_nop 0
	s_nop 0
	s_nop 0
	s_nop 0
	s_nop 0
	s_nop 0
	s_nop 0
	s_nop 0
	s_nop 0
	s_nop 0
	s_nop 0
	s_nop 0
	s_nop 0
	s_nop 0
	s_nop 0
	s_nop 0
	s_nop 0
	s_nop 0
	s_nop 0
	s_nop 0
	s_nop 0
	s_nop 0
	s_nop 0
	s_nop 0
	s_nop 0
	s_nop 0
	s_nop 0
	s_nop 0
	s_nop 0
	s_nop 0
	s_nop 0
	s_nop 0
	s_nop 0
	s_nop 0
	s_nop 0
	s_nop 0
	s_nop 0
	s_nop 0
	s_nop 0
	s_nop 0
	s_nop 0
	s_nop 0
	s_nop 0
	s_nop 0
	s_nop 0
	s_nop 0
	s_nop 0
	s_nop 0
	s_nop 0
	s_nop 0
	s_nop 0
	s_nop 0
	s_nop 0
	s_nop 0
	s_nop 0
	s_nop 0
	s_nop 0
	s_nop 0
	s_nop 0
	s_nop 0
	s_nop 0
	s_nop 0
	s_nop 0
	s_nop 0
	s_nop 0
	s_nop 0
	s_nop 0
	s_nop 0
	s_nop 0
	s_nop 0
	s_nop 0
	s_nop 0
	s_nop 0
	s_nop 0
	s_nop 0
	s_nop 0
	s_nop 0
	s_nop 0
	s_nop 0
	s_nop 0
	s_nop 0
	s_nop 0
	s_nop 0
	s_nop 0
	s_nop 0
	s_nop 0
	s_nop 0
	s_nop 0
	s_nop 0
	s_nop 0
	s_nop 0
	s_nop 0
	s_nop 0
	s_nop 0
	s_nop 0
	s_nop 0
	s_nop 0
	s_nop 0
	s_nop 0
	s_nop 0
	s_nop 0
	s_nop 0
	s_nop 0
	s_nop 0
	s_nop 0
	s_nop 0
	s_nop 0
	s_nop 0
	s_nop 0
	s_nop 0
	s_nop 0
	s_nop 0
	s_nop 0
	s_nop 0
	s_nop 0
	s_nop 0
	s_nop 0
	s_nop 0
	s_nop 0
	s_nop 0
	s_nop 0
	s_nop 0
	s_nop 0
	s_nop 0
	s_nop 0
	s_nop 0
	s_nop 0
	s_nop 0
	s_nop 0
	s_nop 0
	s_nop 0
	s_nop 0
	s_nop 0
	s_nop 0
	s_nop 0
	s_nop 0
	s_nop 0
	s_nop 0
	s_nop 0
	s_nop 0
	s_nop 0
	s_nop 0
	s_nop 0
	s_nop 0
	s_nop 0
	s_nop 0
	s_nop 0
	s_nop 0
	s_nop 0
	s_nop 0
	s_nop 0
	s_nop 0
	s_nop 0
	s_nop 0
	s_nop 0
	s_nop 0
	s_nop 0
	s_nop 0
	s_nop 0
	s_nop 0
	s_nop 0
	s_nop 0
	s_nop 0
	s_nop 0
	s_nop 0
	s_nop 0
	s_nop 0
	s_nop 0
	s_nop 0
	s_nop 0
	s_nop 0
	s_nop 0
	s_nop 0
	s_nop 0
	s_nop 0
	s_nop 0
	s_nop 0
	s_nop 0
	s_nop 0
	s_nop 0
	s_nop 0
	s_nop 0
	s_nop 0
	s_nop 0
	s_nop 0
	s_nop 0
	s_nop 0
	s_nop 0
	s_nop 0
	s_nop 0
	s_nop 0
	s_nop 0
	s_nop 0
	s_nop 0
	s_nop 0
	s_nop 0
	s_nop 0
	s_nop 0
	s_nop 0
	s_nop 0
	s_nop 0
	s_nop 0
	s_nop 0
	s_nop 0
	s_nop 0
	s_nop 0
	s_nop 0
	s_nop 0
	s_nop 0
	s_nop 0
	s_nop 0
	s_nop 0
	s_nop 0
	s_nop 0
	s_nop 0
	s_nop 0
	s_nop 0
	s_nop 0
	s_nop 0
	s_nop 0
	s_nop 0
	s_nop 0
	s_nop 0
	s_nop 0
	s_nop 0
	s_nop 0
	s_nop 0
	s_nop 0
	s_nop 0
	s_nop 0
	s_nop 0
	s_nop 0
	s_nop 0
	s_nop 0
	s_nop 0
	s_nop 0
	s_nop 0
	s_nop 0
	s_nop 0
	s_nop 0
	s_nop 0
	s_nop 0
	s_nop 0
	s_nop 0
	s_nop 0
	s_nop 0
	s_nop 0
	s_nop 0
	s_nop 0
	s_nop 0
	s_nop 0
	s_nop 0
	s_nop 0
	s_nop 0
	s_nop 0
	s_nop 0
	s_nop 0
	s_nop 0
	s_nop 0
	s_nop 0
	s_nop 0
	s_nop 0
	s_nop 0
	s_nop 0
	s_nop 0
	s_nop 0
	s_nop 0
	s_nop 0
	s_nop 0
	s_nop 0
	s_nop 0
	s_nop 0
	s_nop 0
	s_nop 0
	s_nop 0
	s_nop 0
	s_nop 0
	s_nop 0
	s_nop 0
	s_nop 0
	s_nop 0
	s_nop 0
	s_nop 0
	s_nop 0
	s_nop 0
	s_nop 0
	s_nop 0
	s_nop 0
	s_nop 0
	s_nop 0
	s_nop 0
	s_nop 0
	s_nop 0
	s_nop 0
	s_nop 0
	s_nop 0
	s_nop 0
	s_nop 0
	s_nop 0
	s_nop 0
	s_nop 0
	s_nop 0
	s_nop 0
	s_nop 0
	s_nop 0
	s_nop 0
	s_nop 0
	s_nop 0
	s_nop 0
	s_nop 0
	s_nop 0
	s_nop 0
	s_nop 0
	s_nop 0
	s_nop 0
	s_nop 0
	s_nop 0
	s_nop 0
	s_nop 0
	s_nop 0
	s_nop 0
	s_nop 0
	s_nop 0
	s_nop 0
	s_nop 0
	s_nop 0
	s_nop 0
	s_nop 0
	s_nop 0
	s_nop 0
	s_nop 0
	s_nop 0
	s_nop 0
	s_nop 0
	s_nop 0
	s_nop 0
	s_nop 0
	s_nop 0
	s_nop 0
	s_nop 0
	s_nop 0
	s_nop 0
	s_nop 0
	s_nop 0
	s_nop 0
	s_nop 0
	s_nop 0
	s_nop 0
	s_nop 0
	s_nop 0
	s_nop 0
	s_nop 0
	s_nop 0
	s_nop 0
	s_nop 0
	s_nop 0
	s_nop 0
	s_nop 0
	s_nop 0
	s_nop 0
	s_nop 0
	s_nop 0
	s_nop 0
	s_nop 0
	s_nop 0
	s_nop 0
	s_nop 0
	s_nop 0
	s_nop 0
	s_nop 0
	s_nop 0
	s_nop 0
	s_nop 0
	s_nop 0
	s_nop 0
	s_nop 0
	s_nop 0
	s_nop 0
	s_nop 0
	s_nop 0
	s_nop 0
	s_nop 0
	s_nop 0
	s_nop 0
	s_nop 0
	s_nop 0
	s_nop 0
	s_nop 0
	s_nop 0
	s_nop 0
	s_nop 0
	s_nop 0
	s_nop 0
	s_nop 0
	s_nop 0
	s_nop 0
	s_nop 0
	s_nop 0
	s_nop 0
	s_nop 0
	s_nop 0
	s_nop 0
	s_nop 0
	s_nop 0
	s_nop 0
	s_nop 0
	s_nop 0
	s_nop 0
	s_nop 0
	s_nop 0
	s_nop 0
	s_nop 0
	s_nop 0
	s_nop 0
	s_nop 0
	s_nop 0
	s_nop 0
	s_nop 0
	s_nop 0
	s_nop 0
	s_nop 0
	s_nop 0
	s_nop 0
	s_nop 0
	s_nop 0
	s_nop 0
	s_nop 0
	s_nop 0
	s_nop 0
	s_nop 0
	s_nop 0
	s_nop 0
	s_nop 0
	s_nop 0
	s_nop 0
	s_nop 0
	s_nop 0
	s_nop 0
	s_nop 0
	s_nop 0
	s_nop 0
	s_nop 0
	s_nop 0
	s_nop 0
	s_nop 0
	s_nop 0
	s_nop 0
	s_nop 0
	s_nop 0
	s_nop 0
	s_nop 0
	s_nop 0
	s_nop 0
	s_nop 0
	s_nop 0
	s_nop 0
	s_nop 0
	s_nop 0
	s_nop 0
	s_nop 0
	s_nop 0
	s_nop 0
	s_nop 0
	s_nop 0
	s_nop 0
	s_nop 0
	s_nop 0
	s_nop 0
	s_nop 0
	s_nop 0
	s_nop 0
	s_nop 0
	s_nop 0
	s_nop 0
	s_nop 0
	s_nop 0
	s_nop 0
	s_nop 0
	s_nop 0
	s_nop 0
	s_nop 0
	s_nop 0
	s_nop 0
	s_nop 0
	s_nop 0
	s_nop 0
	s_nop 0
	s_nop 0
	s_nop 0
	s_nop 0
	s_nop 0
	s_nop 0
	s_nop 0
	s_nop 0
	s_nop 0
	s_nop 0
	s_nop 0
	s_nop 0
	s_nop 0
	s_nop 0
	s_nop 0
	s_nop 0
	s_nop 0
	s_nop 0
	s_nop 0
	s_nop 0
	s_nop 0
	s_nop 0
	s_nop 0
	s_nop 0
	s_nop 0
	s_nop 0
	s_nop 0
	s_nop 0
	s_nop 0
	s_nop 0
	s_nop 0
	s_nop 0
	s_nop 0
	s_nop 0
	s_nop 0
	s_nop 0
	s_nop 0
	s_nop 0
	s_nop 0
	s_nop 0
	s_nop 0
	s_nop 0
	s_nop 0
	s_nop 0
	s_nop 0
	s_nop 0
	s_nop 0
	s_nop 0
	s_nop 0
	s_nop 0
	s_nop 0
	s_nop 0
	s_nop 0
	s_nop 0
	s_nop 0
	s_nop 0
	s_nop 0
	s_nop 0
	s_nop 0
	s_nop 0
	s_nop 0
	s_nop 0
	s_nop 0
	s_nop 0
	s_nop 0
	s_nop 0
	s_nop 0
	s_nop 0
	s_nop 0
	s_nop 0
	s_nop 0
	s_nop 0
	s_nop 0
	s_nop 0
	s_nop 0
	s_nop 0
	s_nop 0
	s_nop 0
	s_nop 0
	s_nop 0
	s_nop 0
	s_nop 0
	s_nop 0
	s_nop 0
	s_nop 0
	s_nop 0
	s_nop 0
	s_nop 0
	s_nop 0
	s_nop 0
	s_nop 0
	s_nop 0
	s_nop 0
	s_nop 0
	s_nop 0
	s_nop 0
	s_nop 0
	s_nop 0
	s_nop 0
	s_nop 0
	s_nop 0
	s_nop 0
	s_nop 0
	s_nop 0
	s_nop 0
	s_nop 0
	s_nop 0
	s_nop 0
	s_nop 0
	s_nop 0
	s_nop 0
	s_nop 0
	s_nop 0
	s_nop 0
	s_nop 0
	s_nop 0
